# down-projection skinny item: K-slice loaded through a 5-step register ring with counted waits
# speedup vs baseline: 1.0018x; 1.0018x over previous
.LBB0_2650:
	s_and_b32 s14, s8, 0xffffffc0
	s_ashr_i32 s15, s14, 31
	s_add_u32 s22, s14, 0x4000
	v_mov_b32_e32 v0, 0x1600
	s_addc_u32 s23, s15, 0
	s_and_b32 s14, s12, 0x3e0
	v_mad_u64_u32 v[0:1], s[16:17], s22, v0, v[22:23]
	s_lshl_b64 s[18:19], s[22:23], 11
	s_add_u32 s17, s4, s18
	s_mul_i32 s15, s23, 0x1600
	s_addc_u32 s18, s5, s19
	s_lshl_b64 s[22:23], s[22:23], 12
	v_readfirstlane_b32 s21, v27
	v_add_u32_e32 v1, s15, v1
	s_add_u32 s15, s6, s22
	s_addc_u32 s16, s7, s23
	s_ashr_i32 s19, s21, 6
	s_mul_i32 s22, s19, 0x160
	s_ashr_i32 s23, s22, 31
	s_lshl_b64 s[22:23], s[22:23], 1
	s_mul_i32 s48, s14, 0x1600
	v_lshl_add_u64 v[0:1], v[0:1], 0, s[22:23]
	v_lshl_add_u64 v[2:3], v[24:25], 0, s[48:49]
	v_lshl_add_u64 v[36:37], v[0:1], 0, v[16:17]
	v_lshl_add_u64 v[2:3], v[2:3], 0, s[22:23]
	v_add_co_u32_e32 v38, vcc, s89, v36
	v_lshl_add_u64 v[32:33], v[2:3], 0, v[16:17]
	s_nop 0
	v_addc_co_u32_e32 v39, vcc, 0, v37, vcc
	v_add_co_u32_e32 v34, vcc, s89, v32
	s_mov_b32 s24, 0x42000
	s_nop 0
	v_addc_co_u32_e32 v35, vcc, 0, v33, vcc
	v_add_co_u32_e32 v40, vcc, s24, v36
	s_mov_b32 s20, 0x2c000
	s_nop 0
	v_addc_co_u32_e32 v41, vcc, 0, v37, vcc
	v_add_co_u32_e32 v96, vcc, s20, v36
	s_nop 1
	v_addc_co_u32_e32 v97, vcc, 0, v37, vcc
	s_lshl_b32 s20, s14, 1
	s_add_u32 s20, s17, s20
	s_addc_u32 s21, s18, 0
	s_lshl_b32 s14, s14, 2
	s_add_u32 s14, s15, s14
	s_addc_u32 s15, s16, 0
	s_add_i32 s44, s44, s45
	s_add_i32 s8, s8, s9
	s_add_i32 s12, s12, s13
	s_cmpk_gt_i32 s44, 0xff
	global_load_dwordx4 v[100:103], v[36:37], off
	global_load_dwordx4 v[104:107], v[38:39], off
	global_load_dwordx4 v[108:111], v[96:97], off
	global_load_dwordx4 v[112:115], v[40:41], off
	global_load_dwordx4 v[116:119], v[32:33], off
	global_load_dwordx4 v[120:123], v[34:35], off
	global_load_dwordx4 v[124:127], v[36:37], off offset:64
	global_load_dwordx4 v[128:131], v[38:39], off offset:64
	global_load_dwordx4 v[132:135], v[96:97], off offset:64
	global_load_dwordx4 v[136:139], v[40:41], off offset:64
	global_load_dwordx4 v[140:143], v[32:33], off offset:64
	global_load_dwordx4 v[144:147], v[34:35], off offset:64
	global_load_dwordx4 v[148:151], v[36:37], off offset:128
	global_load_dwordx4 v[152:155], v[38:39], off offset:128
	global_load_dwordx4 v[156:159], v[96:97], off offset:128
	global_load_dwordx4 v[160:163], v[40:41], off offset:128
	global_load_dwordx4 v[164:167], v[32:33], off offset:128
	global_load_dwordx4 v[168:171], v[34:35], off offset:128
	global_load_dwordx4 v[172:175], v[36:37], off offset:192
	global_load_dwordx4 v[184:187], v[38:39], off offset:192
	global_load_dwordx4 v[188:191], v[96:97], off offset:192
	global_load_dwordx4 v[192:195], v[40:41], off offset:192
	global_load_dwordx4 v[196:199], v[32:33], off offset:192
	global_load_dwordx4 v[200:203], v[34:35], off offset:192
	global_load_dwordx4 v[204:207], v[36:37], off offset:256
	global_load_dwordx4 v[208:211], v[38:39], off offset:256
	global_load_dwordx4 v[212:215], v[96:97], off offset:256
	global_load_dwordx4 v[216:219], v[40:41], off offset:256
	global_load_dwordx4 v[220:223], v[32:33], off offset:256
	global_load_dwordx4 v[224:227], v[34:35], off offset:256
	s_waitcnt vmcnt(24)
	v_mfma_f32_16x16x32_bf16 v[228:231], v[100:103], v[116:119], 0
	v_mfma_f32_16x16x32_bf16 v[232:235], v[100:103], v[120:123], 0
	v_mfma_f32_16x16x32_bf16 v[64:67], v[104:107], v[116:119], 0
	v_mfma_f32_16x16x32_bf16 v[68:71], v[104:107], v[120:123], 0
	v_mfma_f32_16x16x32_bf16 v[72:75], v[108:111], v[116:119], 0
	v_mfma_f32_16x16x32_bf16 v[76:79], v[108:111], v[120:123], 0
	v_mfma_f32_16x16x32_bf16 v[80:83], v[112:115], v[116:119], 0
	v_mfma_f32_16x16x32_bf16 v[84:87], v[112:115], v[120:123], 0
	global_load_dwordx4 v[100:103], v[36:37], off offset:320
	global_load_dwordx4 v[104:107], v[38:39], off offset:320
	global_load_dwordx4 v[108:111], v[96:97], off offset:320
	global_load_dwordx4 v[112:115], v[40:41], off offset:320
	global_load_dwordx4 v[116:119], v[32:33], off offset:320
	global_load_dwordx4 v[120:123], v[34:35], off offset:320
	s_waitcnt vmcnt(24)
	v_mfma_f32_16x16x32_bf16 v[228:231], v[124:127], v[140:143], v[228:231]
	v_mfma_f32_16x16x32_bf16 v[232:235], v[124:127], v[144:147], v[232:235]
	v_mfma_f32_16x16x32_bf16 v[64:67], v[128:131], v[140:143], v[64:67]
	v_mfma_f32_16x16x32_bf16 v[68:71], v[128:131], v[144:147], v[68:71]
	v_mfma_f32_16x16x32_bf16 v[72:75], v[132:135], v[140:143], v[72:75]
	v_mfma_f32_16x16x32_bf16 v[76:79], v[132:135], v[144:147], v[76:79]
	v_mfma_f32_16x16x32_bf16 v[80:83], v[136:139], v[140:143], v[80:83]
	v_mfma_f32_16x16x32_bf16 v[84:87], v[136:139], v[144:147], v[84:87]
	global_load_dwordx4 v[124:127], v[36:37], off offset:384
	global_load_dwordx4 v[128:131], v[38:39], off offset:384
	global_load_dwordx4 v[132:135], v[96:97], off offset:384
	global_load_dwordx4 v[136:139], v[40:41], off offset:384
	global_load_dwordx4 v[140:143], v[32:33], off offset:384
	global_load_dwordx4 v[144:147], v[34:35], off offset:384
	s_waitcnt vmcnt(24)
	v_mfma_f32_16x16x32_bf16 v[228:231], v[148:151], v[164:167], v[228:231]
	v_mfma_f32_16x16x32_bf16 v[232:235], v[148:151], v[168:171], v[232:235]
	v_mfma_f32_16x16x32_bf16 v[64:67], v[152:155], v[164:167], v[64:67]
	v_mfma_f32_16x16x32_bf16 v[68:71], v[152:155], v[168:171], v[68:71]
	v_mfma_f32_16x16x32_bf16 v[72:75], v[156:159], v[164:167], v[72:75]
	v_mfma_f32_16x16x32_bf16 v[76:79], v[156:159], v[168:171], v[76:79]
	v_mfma_f32_16x16x32_bf16 v[80:83], v[160:163], v[164:167], v[80:83]
	v_mfma_f32_16x16x32_bf16 v[84:87], v[160:163], v[168:171], v[84:87]
	global_load_dwordx4 v[148:151], v[36:37], off offset:448
	global_load_dwordx4 v[152:155], v[38:39], off offset:448
	global_load_dwordx4 v[156:159], v[96:97], off offset:448
	global_load_dwordx4 v[160:163], v[40:41], off offset:448
	global_load_dwordx4 v[164:167], v[32:33], off offset:448
	global_load_dwordx4 v[168:171], v[34:35], off offset:448
	s_waitcnt vmcnt(24)
	v_mfma_f32_16x16x32_bf16 v[228:231], v[172:175], v[196:199], v[228:231]
	v_mfma_f32_16x16x32_bf16 v[232:235], v[172:175], v[200:203], v[232:235]
	v_mfma_f32_16x16x32_bf16 v[64:67], v[184:187], v[196:199], v[64:67]
	v_mfma_f32_16x16x32_bf16 v[68:71], v[184:187], v[200:203], v[68:71]
	v_mfma_f32_16x16x32_bf16 v[72:75], v[188:191], v[196:199], v[72:75]
	v_mfma_f32_16x16x32_bf16 v[76:79], v[188:191], v[200:203], v[76:79]
	v_mfma_f32_16x16x32_bf16 v[80:83], v[192:195], v[196:199], v[80:83]
	v_mfma_f32_16x16x32_bf16 v[84:87], v[192:195], v[200:203], v[84:87]
	global_load_dwordx4 v[172:175], v[36:37], off offset:512
	global_load_dwordx4 v[184:187], v[38:39], off offset:512
	global_load_dwordx4 v[188:191], v[96:97], off offset:512
	global_load_dwordx4 v[192:195], v[40:41], off offset:512
	global_load_dwordx4 v[196:199], v[32:33], off offset:512
	global_load_dwordx4 v[200:203], v[34:35], off offset:512
	s_waitcnt vmcnt(24)
	v_mfma_f32_16x16x32_bf16 v[228:231], v[204:207], v[220:223], v[228:231]
	v_mfma_f32_16x16x32_bf16 v[232:235], v[204:207], v[224:227], v[232:235]
	v_mfma_f32_16x16x32_bf16 v[64:67], v[208:211], v[220:223], v[64:67]
	v_mfma_f32_16x16x32_bf16 v[68:71], v[208:211], v[224:227], v[68:71]
	v_mfma_f32_16x16x32_bf16 v[72:75], v[212:215], v[220:223], v[72:75]
	v_mfma_f32_16x16x32_bf16 v[76:79], v[212:215], v[224:227], v[76:79]
	v_mfma_f32_16x16x32_bf16 v[80:83], v[216:219], v[220:223], v[80:83]
	v_mfma_f32_16x16x32_bf16 v[84:87], v[216:219], v[224:227], v[84:87]
	global_load_dwordx4 v[204:207], v[36:37], off offset:576
	global_load_dwordx4 v[208:211], v[38:39], off offset:576
	global_load_dwordx4 v[212:215], v[96:97], off offset:576
	global_load_dwordx4 v[216:219], v[40:41], off offset:576
	global_load_dwordx4 v[220:223], v[32:33], off offset:576
	global_load_dwordx4 v[224:227], v[34:35], off offset:576
	s_waitcnt vmcnt(24)
	v_mfma_f32_16x16x32_bf16 v[228:231], v[100:103], v[116:119], v[228:231]
	v_mfma_f32_16x16x32_bf16 v[232:235], v[100:103], v[120:123], v[232:235]
	v_mfma_f32_16x16x32_bf16 v[64:67], v[104:107], v[116:119], v[64:67]
	v_mfma_f32_16x16x32_bf16 v[68:71], v[104:107], v[120:123], v[68:71]
	v_mfma_f32_16x16x32_bf16 v[72:75], v[108:111], v[116:119], v[72:75]
	v_mfma_f32_16x16x32_bf16 v[76:79], v[108:111], v[120:123], v[76:79]
	v_mfma_f32_16x16x32_bf16 v[80:83], v[112:115], v[116:119], v[80:83]
	v_mfma_f32_16x16x32_bf16 v[84:87], v[112:115], v[120:123], v[84:87]
	global_load_dwordx4 v[100:103], v[36:37], off offset:640
	global_load_dwordx4 v[104:107], v[38:39], off offset:640
	global_load_dwordx4 v[108:111], v[96:97], off offset:640
	global_load_dwordx4 v[112:115], v[40:41], off offset:640
	global_load_dwordx4 v[116:119], v[32:33], off offset:640
	global_load_dwordx4 v[120:123], v[34:35], off offset:640
	s_waitcnt vmcnt(24)
	v_mfma_f32_16x16x32_bf16 v[228:231], v[124:127], v[140:143], v[228:231]
	v_mfma_f32_16x16x32_bf16 v[232:235], v[124:127], v[144:147], v[232:235]
	v_mfma_f32_16x16x32_bf16 v[64:67], v[128:131], v[140:143], v[64:67]
	v_mfma_f32_16x16x32_bf16 v[68:71], v[128:131], v[144:147], v[68:71]
	v_mfma_f32_16x16x32_bf16 v[72:75], v[132:135], v[140:143], v[72:75]
	v_mfma_f32_16x16x32_bf16 v[76:79], v[132:135], v[144:147], v[76:79]
	v_mfma_f32_16x16x32_bf16 v[80:83], v[136:139], v[140:143], v[80:83]
	v_mfma_f32_16x16x32_bf16 v[84:87], v[136:139], v[144:147], v[84:87]
	s_waitcnt vmcnt(18)
	v_mfma_f32_16x16x32_bf16 v[228:231], v[148:151], v[164:167], v[228:231]
	v_mfma_f32_16x16x32_bf16 v[232:235], v[148:151], v[168:171], v[232:235]
	v_mfma_f32_16x16x32_bf16 v[64:67], v[152:155], v[164:167], v[64:67]
	v_mfma_f32_16x16x32_bf16 v[68:71], v[152:155], v[168:171], v[68:71]
	v_mfma_f32_16x16x32_bf16 v[72:75], v[156:159], v[164:167], v[72:75]
	v_mfma_f32_16x16x32_bf16 v[76:79], v[156:159], v[168:171], v[76:79]
	v_mfma_f32_16x16x32_bf16 v[80:83], v[160:163], v[164:167], v[80:83]
	v_mfma_f32_16x16x32_bf16 v[84:87], v[160:163], v[168:171], v[84:87]
	s_waitcnt vmcnt(12)
	v_mfma_f32_16x16x32_bf16 v[228:231], v[172:175], v[196:199], v[228:231]
	v_mfma_f32_16x16x32_bf16 v[232:235], v[172:175], v[200:203], v[232:235]
	v_mfma_f32_16x16x32_bf16 v[64:67], v[184:187], v[196:199], v[64:67]
	v_mfma_f32_16x16x32_bf16 v[68:71], v[184:187], v[200:203], v[68:71]
	v_mfma_f32_16x16x32_bf16 v[72:75], v[188:191], v[196:199], v[72:75]
	v_mfma_f32_16x16x32_bf16 v[76:79], v[188:191], v[200:203], v[76:79]
	v_mfma_f32_16x16x32_bf16 v[80:83], v[192:195], v[196:199], v[80:83]
	v_mfma_f32_16x16x32_bf16 v[84:87], v[192:195], v[200:203], v[84:87]
	s_waitcnt vmcnt(6)
	v_mfma_f32_16x16x32_bf16 v[228:231], v[204:207], v[220:223], v[228:231]
	v_mfma_f32_16x16x32_bf16 v[232:235], v[204:207], v[224:227], v[232:235]
	v_mfma_f32_16x16x32_bf16 v[64:67], v[208:211], v[220:223], v[64:67]
	v_mfma_f32_16x16x32_bf16 v[68:71], v[208:211], v[224:227], v[68:71]
	v_mfma_f32_16x16x32_bf16 v[72:75], v[212:215], v[220:223], v[72:75]
	v_mfma_f32_16x16x32_bf16 v[76:79], v[212:215], v[224:227], v[76:79]
	v_mfma_f32_16x16x32_bf16 v[80:83], v[216:219], v[220:223], v[80:83]
	v_mfma_f32_16x16x32_bf16 v[84:87], v[216:219], v[224:227], v[84:87]
	s_waitcnt vmcnt(0)
	v_mfma_f32_16x16x32_bf16 v[44:47], v[100:103], v[116:119], v[228:231]
	v_mfma_f32_16x16x32_bf16 v[18:21], v[100:103], v[120:123], v[232:235]
	v_mfma_f32_16x16x32_bf16 v[4:7], v[104:107], v[116:119], v[64:67]
	v_mfma_f32_16x16x32_bf16 v[8:11], v[104:107], v[120:123], v[68:71]
	v_mfma_f32_16x16x32_bf16 v[36:39], v[108:111], v[116:119], v[72:75]
	v_mfma_f32_16x16x32_bf16 v[32:35], v[108:111], v[120:123], v[76:79]
	v_mfma_f32_16x16x32_bf16 v[52:55], v[112:115], v[116:119], v[80:83]
	v_mfma_f32_16x16x32_bf16 v[0:3], v[112:115], v[120:123], v[84:87]
	s_nop 7
	v_lshlrev_b32_e32 v40, 1, v26
	v_mov_b32_e32 v41, v17
	v_lshl_add_u32 v60, s19, 13, v43
	v_add_u32_e32 v61, 0x800, v60
	v_add_u32_e32 v62, 0x1000, v60
	v_add_u32_e32 v63, 0x1800, v60
	v_lshl_add_u64 v[56:57], s[20:21], 0, v[28:29]
	v_lshl_add_u64 v[40:41], v[56:57], 0, v[40:41]
	s_nop 7
	ds_write2_b32 v60, v44, v18 offset1:16
	ds_write2_b32 v60, v45, v19 offset0:32 offset1:48
	ds_write2_b32 v60, v46, v20 offset0:64 offset1:80
	ds_write2_b32 v60, v47, v21 offset0:96 offset1:112
	ds_write2_b32 v61, v4, v8 offset1:16
	ds_write2_b32 v61, v5, v9 offset0:32 offset1:48
	ds_write2_b32 v61, v6, v10 offset0:64 offset1:80
	ds_write2_b32 v61, v7, v11 offset0:96 offset1:112
	ds_write2_b32 v62, v36, v32 offset1:16
	ds_write2_b32 v62, v37, v33 offset0:32 offset1:48
	ds_write2_b32 v62, v38, v34 offset0:64 offset1:80
	ds_write2_b32 v62, v39, v35 offset0:96 offset1:112
	ds_write2_b32 v63, v52, v0 offset1:16
	ds_write2_b32 v63, v53, v1 offset0:32 offset1:48
	ds_write2_b32 v63, v54, v2 offset0:64 offset1:80
	ds_write2_b32 v63, v55, v3 offset0:96 offset1:112
	s_waitcnt lgkmcnt(0)
	s_barrier
	global_load_dwordx2 v[40:41], v[40:41], off
	v_lshlrev_b32_e32 v0, 2, v26
	v_mov_b32_e32 v1, v17
	v_lshl_add_u64 v[2:3], s[14:15], 0, v[30:31]
	v_lshl_add_u64 v[48:49], v[2:3], 0, v[0:1]
	ds_read_b128 v[0:3], v42
	ds_read_b128 v[4:7], v42 offset:8192
	ds_read_b128 v[8:11], v42 offset:16384
	ds_read_b128 v[12:15], v42 offset:24576
	ds_read_b128 v[18:21], v42 offset:32768
	ds_read_b128 v[32:35], v42 offset:40960
	ds_read_b128 v[36:39], v42 offset:49152
	ds_read_b128 v[44:47], v42 offset:57344
	s_waitcnt vmcnt(0)
	v_lshlrev_b32_e32 v50, 16, v40
	v_and_b32_e32 v51, 0xffff0000, v40
	v_lshlrev_b32_e32 v40, 16, v41
	v_and_b32_e32 v41, 0xffff0000, v41
	s_waitcnt lgkmcnt(7)
	v_pk_fma_f32 v[0:1], v[50:51], s[94:95], v[0:1] op_sel_hi:[1,0,1]
	v_pk_fma_f32 v[2:3], v[40:41], s[94:95], v[2:3] op_sel_hi:[1,0,1]
	s_waitcnt lgkmcnt(6)
	v_pk_add_f32 v[0:1], v[4:5], v[0:1]
	v_pk_add_f32 v[2:3], v[6:7], v[2:3]
	s_waitcnt lgkmcnt(5)
	v_pk_add_f32 v[0:1], v[8:9], v[0:1]
	v_pk_add_f32 v[2:3], v[10:11], v[2:3]
	s_waitcnt lgkmcnt(4)
	v_pk_add_f32 v[0:1], v[12:13], v[0:1]
	v_pk_add_f32 v[2:3], v[14:15], v[2:3]
	s_waitcnt lgkmcnt(3)
	v_pk_add_f32 v[0:1], v[18:19], v[0:1]
	v_pk_add_f32 v[2:3], v[20:21], v[2:3]
	s_waitcnt lgkmcnt(2)
	v_pk_add_f32 v[0:1], v[32:33], v[0:1]
	v_pk_add_f32 v[2:3], v[34:35], v[2:3]
	s_waitcnt lgkmcnt(1)
	v_pk_add_f32 v[0:1], v[36:37], v[0:1]
	v_pk_add_f32 v[2:3], v[38:39], v[2:3]
	s_waitcnt lgkmcnt(0)
	v_pk_add_f32 v[0:1], v[44:45], v[0:1]
	v_pk_add_f32 v[2:3], v[46:47], v[2:3]
	global_store_dwordx4 v[48:49], v[0:3], off
	s_barrier
	s_cbranch_scc0 .LBB0_2650
